# v14 + strategy 7.4 mirrored: all per-segment s_setprio flips deleted, one static s_setprio 1 for waves 0-3 at kernel entry
# speedup vs baseline: 1.0012x; 1.0012x over previous
; #define LAS __attribute__((address_space(3)))
; __global__ void __launch_bounds__(NTHR, 2) fwd_kernel(Args a_unused) {
;     extern __shared__ __attribute__((aligned(16))) unsigned char lds_raw[];
;     LAS unsigned char* lds = (LAS unsigned char*)lds_raw;
;     cg::grid_group grid = cg::this_grid();
;     const int G = NWG, bid = blockIdx.x;
;     const int wv = __builtin_amdgcn_readfirstlane(threadIdx.x >> 6);
;     ArgsCP ap = (ArgsCP)__builtin_amdgcn_kernarg_segment_ptr();
_Z10fwd_kernel4Args:
	s_mov_b64 s[46:47], s[0:1]
	v_writelane_b32 v255, 0, 62
	v_and_b32_e32 v1, 0x3ff, v0
	s_mov_b32 s60, s2
	s_add_u32 s2, s46, 0x90
	v_readfirstlane_b32 s0, v1
	s_addc_u32 s3, s47, 0
	v_mbcnt_lo_u32_b32 v2, -1, 0
	v_mbcnt_hi_u32_b32 v2, -1, v2
	s_nop 0
	v_writelane_b32 v252, s0, 0
	s_lshr_b32 s4, s0, 8
	s_cmp_lg_u32 s4, 0
	s_cbranch_scc1 .Lmy_prio_done
	s_setprio 1
